# diff-attn loop: static s_setprio 1 for waves 4-7 during the steady-state loop
# speedup vs baseline: 1.0052x; 1.0025x over previous
; #define SBAR() __builtin_amdgcn_sched_barrier(0)
; __device__ __forceinline__ int v_st(int k, int c) { const int kk = (k & ~0xC) | ((k & 4) << 1) | ((k & 8) >> 1); return ((kk >> 3) * 4 + (c >> 5)) * 512 + ((kk & 7) * 32 + (c & 31)) * 2; }
; __device__ __forceinline__ int v_rd_base(int lane) { return ((lane & 3) << 3) | (((lane >> 2) & 3) << 6) | (((lane >> 4) & 1) << 5) | (((lane >> 5) & 1) << 8); }
; #define VMW() asm volatile("s_waitcnt vmcnt(0)" ::: "memory")
; #define SLOAD_H(Kp, Vp, k0) do { S.st_v0 = load8<TIn>(ROW(Vp, k0, sr)); S.st_v1 = load8<TIn>(ROW(Vp, k0, 32 + sr));              \
;                          S.st_k0 = load8<TIn>(ROW(Kp, k0, sr)); S.st_k1 = load8<TIn>(ROW(Kp, k0, 32 + sr)); } while (0)
; #define SWRITE_HV(bf) do { *(bf16x8*)(V_lds + (bf) * SHM_V + vst0) = S.st_v0; *(bf16x8*)(V_lds + (bf) * SHM_V + vst1) = S.st_v1; } while (0)
; #define SWRITE_H(bf) do { SWRITE_HV(bf); SWRITE_HK(bf); } while (0)
; #define SWRITE_KF(bf) do { *(bf16x8*)(K_lds + (bf) * SHM_K + kws) = pack8(S.sf0, S.sf1); *(bf16x8*)(K_lds + (bf) * SHM_K + kws + 32 * 256) = pack8(S.sf2, S.sf3); } while (0)
; template <class TIn, class TOut>
; __device__ __forceinline__ void causal_swa_block(const BlockRef<TIn, TOut>& cur, const BlockRef<TIn, TOut>& nxt, int skv, int W, char* lds, Seam<TIn>& S) {
;     ...
;     float m_reg = -1e30f, l_reg = 0; f32x16 o[4] = {};
;     const int sr = tid >> 4, sc = (tid & 15) * 8, vst0 = v_st(sr, sc), vst1 = v_st(32 + sr, sc), kws = KSWZ(sr, sc * 2);
;     const int vb0 = (int)(uintptr_t)V_lds + v_rd_base(lane);
;     const TIn* Kh = cur.K; const TIn* Vh = cur.V;
;     ...
;     constexpr int NQL = F32 ? 16 : 8;
;     constexpr bool SK = WSKIP && !F32;
;     ...
;     f32x16 pA0, pA1, pB0, pB1; float mnA, mnB, alA, alB; bf16x8 pa0, pa1, pa2, pa3;
;     if constexpr (F32) { VMW(); SWRITE_VF(0); SBAR(); } else { SWRITE_HV(0); SBAR(); }
;     if (NT > 1) { if constexpr (F32) SLOAD_F((const float*)Kh, KBASE(1)); else SLOAD_H(Kh, Vh, KBASE(1)); }
;     SBAR(); qkt<0, SK>(pA0, pA1, K_lds, r32, hi, S.qr, ACT(0));
;     if constexpr (F32) { if (NT > 1) { VMW(); SWRITE_KF(1); SBAR(); SLOAD_F((const float*)Vh, KBASE(1)); } }
;     MASKT(pA0, pA1, 0); partialSM(pA0, pA1, m_reg, mnA, alA);
;     if (NT > 1) { VMW(); if constexpr (F32) { SWRITE_VF(1); SBAR(); if (NT > 2) SLOAD_F((const float*)Kh, KBASE(2)); } else SWRITE_H(1); }
;     __syncthreads();
.LBB0_1128:
	s_nop 8
	v_max_f32_e32 v50, v19, v19
	v_max_f32_e32 v51, v18, v18
	v_max_f32_e32 v50, v51, v50
	v_max3_f32 v50, v50, v20, v21
	v_max3_f32 v50, v50, v22, v23
	v_max3_f32 v50, v50, v24, v25
	v_max3_f32 v50, v50, v26, v27
	v_max3_f32 v50, v50, v28, v29
	v_max3_f32 v50, v50, v30, v31
	v_max3_f32 v50, v50, v32, v33
	v_max3_f32 v50, v50, v2, v3
	v_max3_f32 v50, v50, v4, v5
	v_max3_f32 v50, v50, v6, v7
	v_max3_f32 v50, v50, v8, v9
	v_max3_f32 v50, v50, v10, v11
	v_max3_f32 v50, v50, v12, v13
	v_max3_f32 v50, v50, v14, v15
	v_max3_f32 v50, v50, v16, v17
	v_mov_b32_e32 v51, v50
	s_nop 1
	v_permlane32_swap_b32_e32 v50, v51
	v_max_f32_e32 v51, v51, v51
	v_max_f32_e32 v50, v50, v50
	v_max_f32_e32 v50, v50, v51
	s_and_b32 s4, s4, 0x3fffffc0
	v_add_f32_e32 v51, 0x7149f2ca, v50
	s_lshl_b32 s4, s4, 2
	v_mul_f32_e32 v51, 0x3db504f3, v51
	v_max_f32_e32 v50, 0xf149f2ca, v50
	s_add_i32 s14, s80, 0xff
	s_add_i32 s4, s4, 0
	v_cmp_ge_f32_e32 vcc, s86, v51
	v_sub_f32_e32 v51, 0xf149f2ca, v50
	s_lshr_b32 s24, s14, 6
	s_add_i32 s4, s4, 0x10000
	s_add_i32 s15, s13, 0xffffc01f
	v_mul_f32_e32 v51, 0x3e0293ee, v51
	v_exp_f32_e32 v51, v51
	s_cmp_eq_u64 vcc, exec
	s_cselect_b64 vcc, -1, 0
	v_cndmask_b32_e32 v178, v50, v216, vcc
	v_mul_f32_e32 v50, 0xbe0293ee, v178
	v_cndmask_b32_e64 v197, v51, 1.0, vcc
	v_mov_b32_e32 v51, v50
	v_fmamk_f32 v18, v18, 0x3e0293ee, v50
	v_fmamk_f32 v19, v19, 0x3e0293ee, v50
	v_fmamk_f32 v20, v20, 0x3e0293ee, v50
	v_fmamk_f32 v21, v21, 0x3e0293ee, v50
	v_fmamk_f32 v22, v22, 0x3e0293ee, v50
	v_fmamk_f32 v23, v23, 0x3e0293ee, v50
	v_fmamk_f32 v24, v24, 0x3e0293ee, v50
	v_fmamk_f32 v25, v25, 0x3e0293ee, v50
	v_fmamk_f32 v26, v26, 0x3e0293ee, v50
	v_fmamk_f32 v27, v27, 0x3e0293ee, v50
	v_fmamk_f32 v28, v28, 0x3e0293ee, v50
	v_fmamk_f32 v29, v29, 0x3e0293ee, v50
	v_fmamk_f32 v30, v30, 0x3e0293ee, v50
	v_fmamk_f32 v31, v31, 0x3e0293ee, v50
	v_fmamk_f32 v32, v32, 0x3e0293ee, v50
	v_fmac_f32_e32 v51, 0x3e0293ee, v33
	v_exp_f32_e32 v170, v18
	v_exp_f32_e32 v171, v19
	v_exp_f32_e32 v172, v20
	v_exp_f32_e32 v173, v21
	v_exp_f32_e32 v174, v22
	v_exp_f32_e32 v176, v23
	v_exp_f32_e32 v175, v24
	v_exp_f32_e32 v177, v25
	v_exp_f32_e32 v162, v26
	v_exp_f32_e32 v163, v27
	v_exp_f32_e32 v164, v28
	v_exp_f32_e32 v166, v29
	v_exp_f32_e32 v165, v30
	v_exp_f32_e32 v167, v31
	v_exp_f32_e32 v168, v32
	v_exp_f32_e32 v169, v51
	s_waitcnt vmcnt(0)
	s_waitcnt vmcnt(3)
	ds_write_b128 v209, v[34:37] offset:16384
	s_waitcnt vmcnt(1)
	ds_write_b128 v210, v[46:49] offset:16384
	ds_write_b128 v217, v[38:41] offset:49152
	s_waitcnt vmcnt(0)
	ds_write_b128 v217, v[42:45] offset:57344
	v_mov_b32_e32 v34, v195
	v_mov_b32_e32 v35, v195
	v_mov_b32_e32 v48, v195
	v_mov_b32_e32 v49, v195
	v_pk_fma_f32 v[118:119], v[16:17], s[50:51], v[50:51] op_sel_hi:[1,0,0]
	v_pk_fma_f32 v[122:123], v[14:15], s[50:51], v[50:51] op_sel_hi:[1,0,0]
	v_pk_fma_f32 v[128:129], v[12:13], s[50:51], v[50:51] op_sel_hi:[1,0,0]
	v_pk_fma_f32 v[114:115], v[10:11], s[50:51], v[50:51] op_sel_hi:[1,0,0]
	v_pk_fma_f32 v[116:117], v[8:9], s[50:51], v[50:51] op_sel_hi:[1,0,0]
	v_pk_fma_f32 v[120:121], v[6:7], s[50:51], v[50:51] op_sel_hi:[1,0,0]
	v_pk_fma_f32 v[124:125], v[4:5], s[50:51], v[50:51] op_sel_hi:[1,0,0]
	v_pk_fma_f32 v[126:127], v[2:3], s[50:51], v[50:51] op_sel_hi:[1,0,0]
	v_mov_b32_e32 v36, v195
	v_mov_b32_e32 v37, v195
	v_mov_b32_e32 v38, v195
	v_mov_b32_e32 v39, v195
	v_mov_b32_e32 v40, v195
	v_mov_b32_e32 v41, v195
	v_mov_b32_e32 v42, v195
	v_mov_b32_e32 v43, v195
	v_mov_b32_e32 v44, v195
	v_mov_b32_e32 v45, v195
	v_mov_b32_e32 v46, v195
	v_mov_b32_e32 v47, v195
	v_mov_b64_e32 v[64:65], v[48:49]
	v_mov_b64_e32 v[18:19], v[34:35]
	v_mov_b64_e32 v[2:3], v[34:35]
	s_mov_b32 s25, 2
	v_lshl_add_u32 v219, v199, 2, s4
	v_lshl_add_u32 v218, v200, 2, s4
	v_add_u32_e32 v222, s12, v201
	v_mov_b32_e32 v221, 0
	s_movk_i32 s26, 0xbf
	v_mov_b32_e32 v194, v203
	v_mov_b64_e32 v[62:63], v[46:47]
	v_mov_b64_e32 v[60:61], v[44:45]
	v_mov_b64_e32 v[58:59], v[42:43]
	v_mov_b64_e32 v[56:57], v[40:41]
	v_mov_b64_e32 v[54:55], v[38:39]
	v_mov_b64_e32 v[52:53], v[36:37]
	v_mov_b64_e32 v[50:51], v[34:35]
	v_mov_b64_e32 v[20:21], v[36:37]
	v_mov_b64_e32 v[22:23], v[38:39]
	v_mov_b64_e32 v[24:25], v[40:41]
	v_mov_b64_e32 v[26:27], v[42:43]
	v_mov_b64_e32 v[28:29], v[44:45]
	v_mov_b64_e32 v[30:31], v[46:47]
	v_mov_b64_e32 v[32:33], v[48:49]
	v_mov_b64_e32 v[4:5], v[36:37]
	v_mov_b64_e32 v[6:7], v[38:39]
	v_mov_b64_e32 v[8:9], v[40:41]
	v_mov_b64_e32 v[10:11], v[42:43]
	v_mov_b64_e32 v[12:13], v[44:45]
	v_mov_b64_e32 v[14:15], v[46:47]
	v_mov_b64_e32 v[16:17], v[48:49]
	s_waitcnt lgkmcnt(0)
	s_barrier
	v_lshlrev_b32_e32 v255, 1, v194
	v_mov_b32_e32 v252, v178
	v_mul_f32_e32 v253, 0xbe0293ee, v178
	v_readfirstlane_b32 s52, v1
	s_nop 3
	s_and_b32 s52, s52, 0x3ff
	s_cmpk_ge_u32 s52, 0x100
	s_cbranch_scc0 .Lattn_prio_skip
	s_setprio 1
; __device__ __forceinline__ void finishSM(f32x16& p0, f32x16& p1, float alpha, float& l_reg, bf16x8& pa0, bf16x8& pa1, bf16x8& pa2, bf16x8& pa3) {
;     for (int r = 0; r < 16; ++r) p1[r] = __builtin_amdgcn_exp2f(p1[r]);
;     float ps = 0; for (int r = 0; r < 16; ++r) ps += p0[r]; for (int r = 0; r < 16; ++r) ps += p1[r];
;     { auto rr = __builtin_amdgcn_permlane32_swap(__float_as_uint(ps), __float_as_uint(ps), false, false);
;       ps = __uint_as_float(rr[0]) + __uint_as_float(rr[1]); }
;     l_reg = l_reg * alpha + ps;
;     ...
;     PK4(p0, 0, pa0); PK4(p0, 8, pa1); PK4(p1, 0, pa2); PK4(p1, 8, pa3);
; template <int KB, bool SK>
; __device__ __forceinline__ void qkt(f32x16& p0, f32x16& p1, const char* K_lds, int r32, int hi, const bf16x8* qr, bool act) {
;     if (SK && !act) { const float NEG = -__builtin_inff();
; #pragma unroll
;         for (int r = 0; r < 16; ++r) { p0[r] = NEG; p1[r] = NEG; } return; }
;     p0 = f32x16{}; p1 = f32x16{};
;     const char* kb[4];
; #pragma unroll
;     for (int dd = 0; dd < 4; ++dd) kb[dd] = K_lds + KB * SHM_K + KSWZ(r32, (dd * 16 + hi * 8) * 2);
; #pragma unroll
;     for (int d0 = 0; d0 < 8; ++d0) { const char* a = kb[d0 & 3] + (d0 >> 2) * 128;
;         bf16x8 b0 = *reinterpret_cast<const bf16x8*>(a);
;         bf16x8 b1 = *reinterpret_cast<const bf16x8*>(a + 32 * 256);
;         const bf16x8 qf = qr[d0];
;         p0 = __builtin_amdgcn_mfma_f32_32x32x16_bf16(b0, qf, p0, 0, 0, 0);
;         p1 = __builtin_amdgcn_mfma_f32_32x32x16_bf16(b1, qf, p1, 0, 0, 0); }
.Lattn_prio_skip:
.LBB0_1129:
	ds_read_b128 v[180:183], v211 offset:49152
	ds_read_b128 v[184:187], v211 offset:57344
	ds_read_b128 v[188:191], v212 offset:49152
	ds_read_b128 v[228:231], v212 offset:57344
	ds_read_b128 v[232:235], v213 offset:49152
	ds_read_b128 v[236:239], v213 offset:57344
	ds_read_b128 v[240:243], v214 offset:49152
	ds_read_b128 v[244:247], v214 offset:57344
	v_exp_f32_e32 v126, v126
	v_exp_f32_e32 v127, v127
	v_exp_f32_e32 v124, v124
	v_exp_f32_e32 v125, v125
	v_exp_f32_e32 v120, v120
	v_exp_f32_e32 v121, v121
	v_exp_f32_e32 v116, v116
	v_exp_f32_e32 v117, v117
	v_exp_f32_e32 v114, v114
	v_exp_f32_e32 v115, v115
	v_exp_f32_e32 v128, v128
	v_exp_f32_e32 v129, v129
	v_exp_f32_e32 v122, v122
	v_exp_f32_e32 v123, v123
	v_exp_f32_e32 v118, v118
	v_exp_f32_e32 v119, v119
	s_add_i32 s4, s26, 0xffffff81
	s_sub_i32 s5, s26, 64
	s_waitcnt lgkmcnt(7)
	v_mfma_f32_32x32x16_bf16 v[86:101], v[180:183], v[158:161], 0
	ds_read_b128 v[180:183], v211 offset:49280
	v_add_f32_e32 v179, 0, v170
	v_add_f32_e32 v179, v171, v179
	v_add_f32_e32 v179, v172, v179
	v_add_f32_e32 v179, v173, v179
	s_waitcnt lgkmcnt(7)
	v_mfma_f32_32x32x16_bf16 v[70:85], v[184:187], v[158:161], 0
	ds_read_b128 v[184:187], v211 offset:57472
	v_add_f32_e32 v179, v174, v179
	v_add_f32_e32 v179, v176, v179
	v_add_f32_e32 v179, v175, v179
	v_add_f32_e32 v179, v177, v179
	s_waitcnt lgkmcnt(7)
	v_mfma_f32_32x32x16_bf16 v[86:101], v[188:191], v[154:157], v[86:101]
	ds_read_b128 v[188:191], v212 offset:49280
	v_add_f32_e32 v179, v162, v179
	v_add_f32_e32 v179, v163, v179
	v_add_f32_e32 v110, v164, v179
	v_add_f32_e32 v110, v166, v110
	s_waitcnt lgkmcnt(7)
	v_mfma_f32_32x32x16_bf16 v[70:85], v[228:231], v[154:157], v[70:85]
	ds_read_b128 v[228:231], v212 offset:57472
	v_add_f32_e32 v110, v165, v110
	v_add_f32_e32 v110, v167, v110
	v_add_f32_e32 v110, v168, v110
	v_add_f32_e32 v110, v169, v110
	s_waitcnt lgkmcnt(7)
	v_mfma_f32_32x32x16_bf16 v[86:101], v[232:235], v[150:153], v[86:101]
	ds_read_b128 v[232:235], v213 offset:49280
	v_add_f32_e32 v110, v126, v110
	v_add_f32_e32 v102, v127, v110
	v_add_f32_e32 v102, v124, v102
	v_add_f32_e32 v102, v125, v102
	s_waitcnt lgkmcnt(7)
	v_mfma_f32_32x32x16_bf16 v[70:85], v[236:239], v[150:153], v[70:85]
	ds_read_b128 v[236:239], v213 offset:57472
	v_add_f32_e32 v102, v120, v102
	v_add_f32_e32 v102, v121, v102
	v_add_f32_e32 v102, v116, v102
	v_add_f32_e32 v102, v117, v102
	s_waitcnt lgkmcnt(7)
	v_mfma_f32_32x32x16_bf16 v[86:101], v[240:243], v[134:137], v[86:101]
	ds_read_b128 v[240:243], v214 offset:49280
	v_add_f32_e32 v102, v114, v102
	v_add_f32_e32 v102, v115, v102
	v_add_f32_e32 v102, v128, v102
	v_add_f32_e32 v102, v129, v102
	s_waitcnt lgkmcnt(7)
	v_mfma_f32_32x32x16_bf16 v[70:85], v[244:247], v[134:137], v[70:85]
	ds_read_b128 v[244:247], v214 offset:57472
	v_add_f32_e32 v102, v122, v102
	v_add_f32_e32 v102, v123, v102
	v_add_f32_e32 v102, v118, v102
	v_add_f32_e32 v223, v119, v102
	s_waitcnt lgkmcnt(7)
	v_mfma_f32_32x32x16_bf16 v[86:101], v[180:183], v[138:141], v[86:101]
	v_mov_b32_e32 v224, v223
	s_nop 1
	v_permlane32_swap_b32_e32 v223, v224
	v_cvt_pk_bf16_f32 v102, v170, v171
	v_cvt_pk_bf16_f32 v103, v172, v173
	s_waitcnt lgkmcnt(6)
	v_mfma_f32_32x32x16_bf16 v[70:85], v[184:187], v[138:141], v[70:85]
	v_cvt_pk_bf16_f32 v104, v174, v176
	v_cvt_pk_bf16_f32 v105, v175, v177
	v_cvt_pk_bf16_f32 v66, v162, v163
	v_cvt_pk_bf16_f32 v67, v164, v166
	s_waitcnt lgkmcnt(5)
	v_mfma_f32_32x32x16_bf16 v[86:101], v[188:191], v[142:145], v[86:101]
	v_cvt_pk_bf16_f32 v68, v165, v167
	v_cvt_pk_bf16_f32 v69, v168, v169
	v_cvt_pk_bf16_f32 v106, v126, v127
	s_waitcnt lgkmcnt(4)
	v_mfma_f32_32x32x16_bf16 v[70:85], v[228:231], v[142:145], v[70:85]
	v_cvt_pk_bf16_f32 v107, v124, v125
	v_cvt_pk_bf16_f32 v108, v120, v121
	v_cvt_pk_bf16_f32 v109, v116, v117
	s_waitcnt lgkmcnt(3)
	v_mfma_f32_32x32x16_bf16 v[86:101], v[232:235], v[146:149], v[86:101]
	v_cvt_pk_bf16_f32 v110, v114, v115
	v_cvt_pk_bf16_f32 v111, v128, v129
	v_cvt_pk_bf16_f32 v112, v122, v123
	s_waitcnt lgkmcnt(2)
	v_mfma_f32_32x32x16_bf16 v[70:85], v[236:239], v[146:149], v[70:85]
	v_cvt_pk_bf16_f32 v113, v118, v119
	s_nop 1
	v_permlane32_swap_b32_e32 v102, v104
	v_permlane32_swap_b32_e32 v103, v105
	s_waitcnt lgkmcnt(1)
	v_mfma_f32_32x32x16_bf16 v[86:101], v[240:243], v[130:133], v[86:101]
	v_permlane32_swap_b32_e32 v66, v68
	v_permlane32_swap_b32_e32 v67, v69
	v_permlane32_swap_b32_e32 v106, v108
	s_waitcnt lgkmcnt(0)
	v_mfma_f32_32x32x16_bf16 v[70:85], v[244:247], v[130:133], v[70:85]
	v_permlane32_swap_b32_e32 v107, v109
	v_permlane32_swap_b32_e32 v110, v112
	v_permlane32_swap_b32_e32 v111, v113
	v_add_u32_e32 v114, 0x2000, v255
	global_load_dwordx4 v[162:165], v255, s[42:43]
	global_load_dwordx4 v[166:169], v114, s[42:43]
	global_load_dwordx4 v[170:173], v255, s[22:23]
	global_load_dwordx4 v[174:177], v114, s[22:23]
	s_cmp_le_i32 s5, s13
	s_cselect_b64 s[52:53], -1, 0
	s_cmp_gt_i32 s4, s15
	s_cselect_b64 s[4:5], -1, 0
	s_and_b64 s[4:5], s[52:53], s[4:5]
	s_and_b64 vcc, exec, s[4:5]
	ds_read_b64_tr_b16 v[114:115], v202 offset:0x0
	ds_read_b64_tr_b16 v[116:117], v202 offset:0x800
	ds_read_b64_tr_b16 v[118:119], v202 offset:0x1000
	ds_read_b64_tr_b16 v[120:121], v202 offset:0x1800
	ds_read_b64_tr_b16 v[122:123], v202 offset:0x2000
	ds_read_b64_tr_b16 v[124:125], v202 offset:0x2800
	ds_read_b64_tr_b16 v[126:127], v202 offset:0x3000
	ds_read_b64_tr_b16 v[128:129], v202 offset:0x3800
	ds_read_b64_tr_b16 v[182:183], v202 offset:0x200
	ds_read_b64_tr_b16 v[184:185], v202 offset:0xa00
	ds_read_b64_tr_b16 v[186:187], v202 offset:0x1200
	ds_read_b64_tr_b16 v[188:189], v202 offset:0x1a00
	ds_read_b64_tr_b16 v[190:191], v202 offset:0x2200
	ds_read_b64_tr_b16 v[192:193], v202 offset:0x2a00
	s_cbranch_vccnz .Lh1_nomask
; __device__ __forceinline__ void mask_tile(f32x16& p0, f32x16& p1, int dq, unsigned W) {
;     const float NEG = -__builtin_inff();
; #pragma unroll
;     for (int r = 0; r < 16; ++r) {
;         const int c = (r & 3) + 8 * (r >> 2);
;         if ((unsigned)(dq - c) >= W) p0[r] = NEG;
;         if ((unsigned)(dq - c - 32) >= W) p1[r] = NEG;
;     }
; }
	v_add_u32_e32 v226, s80, v222
	v_subrev_u32_e32 v240, 64, v226
	v_cmp_gt_u32_e32 vcc, s85, v240
	v_add_u32_e32 v240, 0xffffffa0, v226
	s_nop 0
	v_cndmask_b32_e32 v86, v215, v86, vcc
	v_cmp_gt_u32_e32 vcc, s85, v240
	v_add_u32_e32 v240, 0xffffffbf, v226
	s_nop 0
	v_cndmask_b32_e32 v70, v215, v70, vcc
	v_cmp_gt_u32_e32 vcc, s85, v240
	v_add_u32_e32 v240, 0xffffff9f, v226
	s_nop 0
	v_cndmask_b32_e32 v87, v215, v87, vcc
	v_cmp_gt_u32_e32 vcc, s85, v240
	v_add_u32_e32 v240, 0xffffffbe, v226
	s_nop 0
	v_cndmask_b32_e32 v71, v215, v71, vcc
	v_cmp_gt_u32_e32 vcc, s85, v240
	v_add_u32_e32 v240, 0xffffff9e, v226
	s_nop 0
	v_cndmask_b32_e32 v88, v215, v88, vcc
	v_cmp_gt_u32_e32 vcc, s85, v240
	v_add_u32_e32 v240, 0xffffffbd, v226
	s_nop 0
	v_cndmask_b32_e32 v72, v215, v72, vcc
	v_cmp_gt_u32_e32 vcc, s85, v240
	v_add_u32_e32 v240, 0xffffff9d, v226
	s_nop 0
	v_cndmask_b32_e32 v89, v215, v89, vcc
	v_cmp_gt_u32_e32 vcc, s85, v240
	v_add_u32_e32 v240, 0xffffffb8, v226
	s_nop 0
	v_cndmask_b32_e32 v73, v215, v73, vcc
	v_cmp_gt_u32_e32 vcc, s85, v240
	v_add_u32_e32 v240, 0xffffff98, v226
	s_nop 0
	v_cndmask_b32_e32 v90, v215, v90, vcc
	v_cmp_gt_u32_e32 vcc, s85, v240
	v_add_u32_e32 v240, 0xffffffb7, v226
	s_nop 0
	v_cndmask_b32_e32 v74, v215, v74, vcc
	v_cmp_gt_u32_e32 vcc, s85, v240
	v_add_u32_e32 v240, 0xffffff97, v226
	s_nop 0
	v_cndmask_b32_e32 v91, v215, v91, vcc
	v_cmp_gt_u32_e32 vcc, s85, v240
	v_add_u32_e32 v240, 0xffffffb6, v226
	s_nop 0
	v_cndmask_b32_e32 v75, v215, v75, vcc
	v_cmp_gt_u32_e32 vcc, s85, v240
	v_add_u32_e32 v240, 0xffffff96, v226
	s_nop 0
	v_cndmask_b32_e32 v92, v215, v92, vcc
	v_cmp_gt_u32_e32 vcc, s85, v240
	v_add_u32_e32 v240, 0xffffffb5, v226
	s_nop 0
	v_cndmask_b32_e32 v76, v215, v76, vcc
	v_cmp_gt_u32_e32 vcc, s85, v240
	v_add_u32_e32 v240, 0xffffff95, v226
	s_nop 0
	v_cndmask_b32_e32 v93, v215, v93, vcc
	v_cmp_gt_u32_e32 vcc, s85, v240
	v_add_u32_e32 v240, 0xffffffb0, v226
	s_nop 0
	v_cndmask_b32_e32 v77, v215, v77, vcc
	v_cmp_gt_u32_e32 vcc, s85, v240
	v_add_u32_e32 v240, 0xffffff90, v226
	s_nop 0
	v_cndmask_b32_e32 v94, v215, v94, vcc
	v_cmp_gt_u32_e32 vcc, s85, v240
	v_add_u32_e32 v240, 0xffffffaf, v226
	s_nop 0
	v_cndmask_b32_e32 v78, v215, v78, vcc
	v_cmp_gt_u32_e32 vcc, s85, v240
	v_add_u32_e32 v240, 0xffffff8f, v226
	s_nop 0
	v_cndmask_b32_e32 v95, v215, v95, vcc
	v_cmp_gt_u32_e32 vcc, s85, v240
	v_add_u32_e32 v240, 0xffffffae, v226
	s_nop 0
	v_cndmask_b32_e32 v79, v215, v79, vcc
	v_cmp_gt_u32_e32 vcc, s85, v240
	v_add_u32_e32 v240, 0xffffff8e, v226
	s_nop 0
	v_cndmask_b32_e32 v96, v215, v96, vcc
	v_cmp_gt_u32_e32 vcc, s85, v240
	v_add_u32_e32 v240, 0xffffffad, v226
	s_nop 0
	v_cndmask_b32_e32 v80, v215, v80, vcc
	v_cmp_gt_u32_e32 vcc, s85, v240
	v_add_u32_e32 v240, 0xffffff8d, v226
	s_nop 0
	v_cndmask_b32_e32 v97, v215, v97, vcc
	v_cmp_gt_u32_e32 vcc, s85, v240
	v_add_u32_e32 v240, 0xffffffa8, v226
	s_nop 0
	v_cndmask_b32_e32 v81, v215, v81, vcc
	v_cmp_gt_u32_e32 vcc, s85, v240
	v_add_u32_e32 v240, 0xffffff88, v226
	s_nop 0
	v_cndmask_b32_e32 v98, v215, v98, vcc
	v_cmp_gt_u32_e32 vcc, s85, v240
	v_add_u32_e32 v240, 0xffffffa7, v226
	s_nop 0
	v_cndmask_b32_e32 v82, v215, v82, vcc
	v_cmp_gt_u32_e32 vcc, s85, v240
	v_add_u32_e32 v240, 0xffffff87, v226
	s_nop 0
	v_cndmask_b32_e32 v99, v215, v99, vcc
	v_cmp_gt_u32_e32 vcc, s85, v240
	v_add_u32_e32 v240, 0xffffffa6, v226
	s_nop 0
	v_cndmask_b32_e32 v83, v215, v83, vcc
	v_cmp_gt_u32_e32 vcc, s85, v240
	v_add_u32_e32 v240, 0xffffff86, v226
	s_nop 0
	v_cndmask_b32_e32 v100, v215, v100, vcc
	v_cmp_gt_u32_e32 vcc, s85, v240
	v_add_u32_e32 v240, 0xffffffa5, v226
	s_nop 0
	v_cndmask_b32_e32 v84, v215, v84, vcc
	v_cmp_gt_u32_e32 vcc, s85, v240
	v_add_u32_e32 v240, 0xffffff85, v226
	s_nop 0
	v_cndmask_b32_e32 v101, v215, v101, vcc
	v_cmp_gt_u32_e32 vcc, s85, v240
	s_nop 1
	v_cndmask_b32_e32 v85, v215, v85, vcc

; #define SBAR() __builtin_amdgcn_sched_barrier(0)
; #define ACT(t) (KBASE(t) <= qlo + QBLK - 1 && KBASE(t) + KVBLK - 1 >= qlo - W + 1)
; template <class TIn, class TOut>
; __device__ __forceinline__ void causal_swa_block(const BlockRef<TIn, TOut>& cur, const BlockRef<TIn, TOut>& nxt, int skv, int W, char* lds, Seam<TIn>& S) {
;     ...
;     const bool even = (NT & 1) == 0;
;     if (even) { SBAR(); qkt<1, SK>(pB0, pB1, K_lds, r32, hi, S.qr, ACT(NT - 1)); SBAR(); }
.Lattn_exit:
	v_mov_b32_e32 v178, v252
	v_mov_b32_e32 v179, v254
	s_setprio 0
